# GEMM3 tile header: full vmcnt(0) drain after the hoisted ssq loads removed (loads ride under the K-loop's counted waits)
# speedup vs baseline: 1.0059x; 1.0026x over previous
;     __host__ __device__ bool next(int i, Unit& u) const { const int L = i * G + c; if (L >= 4 * nM) return false; u.pm = L >> 2; u.pn = 0; u.kq = L & 3; return true; }
; #define PG8_STAGE(bufoff, gbase, voff) do { _Pragma("unroll") for (int _i = 0; _i < 2; ++_i) \
;         __builtin_amdgcn_global_load_lds((const unsigned*)((const char*)(gbase) + (voff)[_i]), (PG8_LAS unsigned*)(lds + (bufoff) + ldsw + _i * 8192), 16, 0, 0); } while (0)
; #define PG8_LDA(dst, b, h) do { _Pragma("unroll") for (int m = 0; m < 4; ++m) _Pragma("unroll") for (int k = 0; k < 2; ++k) dst[m][k] = *(const PG8_LAS bf16x8*)(lds + PG8_SA(b, h) + aoff + m * 2048 + k * 1024); } while (0)
; #define PG8_WAIT_V(n) asm volatile("s_waitcnt vmcnt(" #n ")" ::: "memory")
; #define PG8_WAIT_L(n) asm volatile("s_waitcnt lgkmcnt(" #n ")" ::: "memory")
;     DI void operator()(const f32x4 (&acc)[2][2][4][2], const Unit& u, int wr, int wc, int fr, int fq) const {
;     ...
;             for (int m = 0; m < 4; ++m) rs[ai][m] = ssq ? __builtin_amdgcn_rsqf(ssq[row0 + ai * HALF + m * 16] * (1.0f / 4096.0f) + 1e-6f) : 1.0f;
; template <class Epi, class Sched, bool ALIGN_EPI = false, bool SP2 = false>
; __device__ __forceinline__ void gemm_phase(PG8_LAS unsigned char* lds, const Gemm g, const Sched& S, const Epi& E) {
;     ...
;         const bool has_next = S.next(ui + 1, nxt);
;         const char* nA = has_next ? (const char*)g.A + (size_t)nxt.pm * tstepA + nxt.kq * g.kq_bytes : cA; const char* nB = has_next ? (const char*)g.Bt + (size_t)nxt.pn * tstepB + nxt.kq * g.kq_bytes : cB;
;         for (int t = 0; t < nt; t += 2) {
;             const bool last = (t == nt - 2);
;             const char* a1 = cA + (size_t)(t + 1) * kstep + (t >= g.kj_t ? g.kj_bytes : 0);
;             const char* a2 = last ? nA : cA + (size_t)(t + 2) * kstep + (t + 2 >= g.kj_t ? g.kj_bytes : 0); const char* b2 = last ? nB : cB + (size_t)(t + 2) * kstep;
;             const char* a3 = a2 + kstep; const char* b3 = b2 + kstep;
;             if (last && has_next) S.a_ready(nxt);
;             if constexpr (Epi::MIDK) { if (t == g.kj_t) E.midk(acc, cur, wr, fr); }
;             if constexpr (SP2) {
;             PG8_LDB(B0, 0, 0); PG8_LDB(B1, 0, 1); PG8_SCHED; PG8_LDA(At, 0, 0); PG8_STAGE(PG8_SA(1, 1), a1 + hstepA, voffA);
;             PG8_WAIT_V(8); PG8_WAIT_L(0); PG8_BAR; PG8_MMA(0, 0, At, B0); PG8_MMA(0, 1, At, B1); PG8_BAR; PG8_SCHED;
.LBB0_524:
	s_ashr_i32 s15, s14, 31
	s_lshl_b64 s[16:17], s[14:15], 21
	s_add_u32 s16, s42, s16
	s_addc_u32 s17, s43, s17
	s_and_b64 s[18:19], s[0:1], exec
	s_cselect_b32 s15, s17, s23
	s_cselect_b32 s50, s16, s22
	s_ashr_i32 s13, s12, 31
	s_lshl_b64 s[18:19], s[12:13], 21
	v_readlane_b32 s26, v253, 37
	v_readlane_b32 s27, v253, 38
	s_add_u32 s18, s26, s18
	s_addc_u32 s19, s27, s19
	s_and_b64 s[26:27], s[0:1], exec
	s_cselect_b32 s13, s19, s25
	s_cselect_b32 s51, s18, s24
	s_add_u32 s22, s22, 0x100080
	s_addc_u32 s23, s23, 0
	s_add_u32 s52, s24, 0x100
	s_addc_u32 s53, s25, 0
	s_waitcnt lgkmcnt(0)
	s_mov_b32 s60, -2
	v_lshl_add_u32 v244, s20, 8, v157
	v_ashrrev_i32_e32 v245, 31, v244
	v_lshl_add_u64 v[244:245], v[244:245], 2, s[8:9]
	global_load_dword v236, v[244:245], off
	global_load_dword v237, v[244:245], off offset:64
	global_load_dword v238, v[244:245], off offset:128
	global_load_dword v239, v[244:245], off offset:192
	global_load_dword v240, v[244:245], off offset:512
	global_load_dword v241, v[244:245], off offset:576
	global_load_dword v242, v[244:245], off offset:640
	global_load_dword v243, v[244:245], off offset:704
	s_nop 0
	ds_read_b128 v[146:149], v160
	ds_read_b128 v[168:171], v160 offset:1024
	ds_read_b128 v[172:175], v160 offset:2048
	ds_read_b128 v[176:179], v160 offset:3072
	ds_read_b128 v[180:183], v161
	ds_read_b128 v[184:187], v161 offset:1024
	ds_read_b128 v[188:191], v161 offset:2048
	ds_read_b128 v[192:195], v161 offset:3072
	s_add_u32 s24, s22, 0xfff00080
	s_addc_u32 s25, s23, -1
	s_cmp_eq_u32 s60, 60
	s_cselect_b32 s27, s15, s25
	s_cselect_b32 s26, s50, s24
	s_cselect_b32 s25, s13, s53
	s_cselect_b32 s24, s51, s52
	s_add_u32 s98, s24, 0x80
	s_addc_u32 s99, s25, 0
	s_add_u32 s100, s26, 0x80
	s_addc_u32 s101, s27, 0
	s_add_i32 m0, s21, 0xc000
	ds_read_b128 v[196:199], v162
	ds_read_b128 v[200:203], v162 offset:1024
	ds_read_b128 v[204:207], v162 offset:2048
	ds_read_b128 v[208:211], v162 offset:3072
	ds_read_b128 v[212:215], v162 offset:4096
	ds_read_b128 v[216:219], v162 offset:5120
	ds_read_b128 v[220:223], v162 offset:6144
	ds_read_b128 v[224:227], v162 offset:7168
	global_load_lds_dwordx4 v138, s[22:23]
	s_add_i32 m0, s21, 0xe000
	s_nop 0
	global_load_lds_dwordx4 v140, s[22:23]
	s_waitcnt vmcnt(8)
	s_waitcnt lgkmcnt(0)
	s_barrier
	s_setprio 1
	s_waitcnt lgkmcnt(0)
	v_mfma_f32_16x16x32_bf16 v[126:129], v[146:149], v[196:199], 0
	v_mfma_f32_16x16x32_bf16 v[126:129], v[168:171], v[200:203], v[126:129]
	v_mfma_f32_16x16x32_bf16 v[122:125], v[176:179], v[200:203], 0
	v_mfma_f32_16x16x32_bf16 v[122:125], v[172:175], v[196:199], v[122:125]
	v_mfma_f32_16x16x32_bf16 v[114:117], v[172:175], v[204:207], 0
	v_mfma_f32_16x16x32_bf16 v[114:117], v[176:179], v[208:211], v[114:117]
	v_mfma_f32_16x16x32_bf16 v[118:121], v[168:171], v[208:211], 0
	v_mfma_f32_16x16x32_bf16 v[118:121], v[146:149], v[204:207], v[118:121]
	v_mfma_f32_16x16x32_bf16 v[110:113], v[146:149], v[212:215], 0
	v_mfma_f32_16x16x32_bf16 v[110:113], v[168:171], v[216:219], v[110:113]
	v_mfma_f32_16x16x32_bf16 v[98:101], v[176:179], v[216:219], 0
	v_mfma_f32_16x16x32_bf16 v[98:101], v[172:175], v[212:215], v[98:101]
	v_mfma_f32_16x16x32_bf16 v[78:81], v[172:175], v[220:223], 0
	v_mfma_f32_16x16x32_bf16 v[78:81], v[176:179], v[224:227], v[78:81]
	v_mfma_f32_16x16x32_bf16 v[82:85], v[168:171], v[224:227], 0
	v_mfma_f32_16x16x32_bf16 v[82:85], v[146:149], v[220:223], v[82:85]
	v_mfma_f32_16x16x32_bf16 v[106:109], v[180:183], v[196:199], 0
	v_mfma_f32_16x16x32_bf16 v[106:109], v[184:187], v[200:203], v[106:109]
	v_mfma_f32_16x16x32_bf16 v[102:105], v[192:195], v[200:203], 0
	v_mfma_f32_16x16x32_bf16 v[102:105], v[188:191], v[196:199], v[102:105]
	v_mfma_f32_16x16x32_bf16 v[90:93], v[188:191], v[204:207], 0
	v_mfma_f32_16x16x32_bf16 v[90:93], v[192:195], v[208:211], v[90:93]
	v_mfma_f32_16x16x32_bf16 v[94:97], v[184:187], v[208:211], 0
	v_mfma_f32_16x16x32_bf16 v[94:97], v[180:183], v[204:207], v[94:97]
	v_mfma_f32_16x16x32_bf16 v[86:89], v[180:183], v[212:215], 0
	v_mfma_f32_16x16x32_bf16 v[86:89], v[184:187], v[216:219], v[86:89]
	v_mfma_f32_16x16x32_bf16 v[74:77], v[192:195], v[216:219], 0
	v_mfma_f32_16x16x32_bf16 v[74:77], v[188:191], v[212:215], v[74:77]
	v_mfma_f32_16x16x32_bf16 v[66:69], v[188:191], v[220:223], 0
	v_mfma_f32_16x16x32_bf16 v[66:69], v[192:195], v[224:227], v[66:69]
	s_setprio 2
	s_barrier
	v_mfma_f32_16x16x32_bf16 v[70:73], v[184:187], v[224:227], 0
	v_mfma_f32_16x16x32_bf16 v[70:73], v[180:183], v[220:223], v[70:73]
	s_setprio 0
	s_add_i32 s61, s38, s3
	s_mov_b32 m0, s61
	ds_read_b128 v[196:199], v162 offset:16384
	ds_read_b128 v[200:203], v162 offset:17408
	ds_read_b128 v[204:207], v162 offset:18432
	ds_read_b128 v[208:211], v162 offset:19456
	ds_read_b128 v[212:215], v162 offset:20480
	ds_read_b128 v[216:219], v162 offset:21504
	ds_read_b128 v[220:223], v162 offset:22528
	ds_read_b128 v[224:227], v162 offset:23552
	global_load_lds_dwordx4 v136, s[24:25]
	s_add_i32 m0, s61, 0x2000
	s_add_u32 s62, s24, 0x100000
	s_addc_u32 s63, s25, 0
	s_add_i32 s61, s39, s3
	global_load_lds_dwordx4 v134, s[24:25]
	s_mov_b32 m0, s61
	s_nop 0
	global_load_lds_dwordx4 v136, s[62:63]
	s_add_i32 m0, s61, 0x2000
	s_nop 0
	global_load_lds_dwordx4 v134, s[62:63]
	s_mov_b32 m0, s21
	s_nop 0
	global_load_lds_dwordx4 v130, s[26:27]
	s_mov_b32 m0, s30
	s_nop 0
	global_load_lds_dwordx4 v132, s[26:27]
	s_waitcnt vmcnt(8)
	s_waitcnt lgkmcnt(0)
	s_barrier
; #define PG8_STAGE(bufoff, gbase, voff) do { _Pragma("unroll") for (int _i = 0; _i < 2; ++_i) \
;         __builtin_amdgcn_global_load_lds((const unsigned*)((const char*)(gbase) + (voff)[_i]), (PG8_LAS unsigned*)(lds + (bufoff) + ldsw + _i * 8192), 16, 0, 0); } while (0)
; #define PG8_LDA(dst, b, h) do { _Pragma("unroll") for (int m = 0; m < 4; ++m) _Pragma("unroll") for (int k = 0; k < 2; ++k) dst[m][k] = *(const PG8_LAS bf16x8*)(lds + PG8_SA(b, h) + aoff + m * 2048 + k * 1024); } while (0)
; #define PG8_MMA(ai, bj, At, Bt) do { __builtin_amdgcn_s_setprio(1); _Pragma("unroll") for (int m = 0; m < 4; ++m) _Pragma("unroll") for (int n = 0; n < 2; ++n) _Pragma("unroll") for (int k = 0; k < 2; ++k) \
;         acc[ai][bj][m][n] = __builtin_amdgcn_mfma_f32_16x16x32_bf16(Bt[n][k], At[m][k], acc[ai][bj][m][n], 0, 0, 0); __builtin_amdgcn_s_setprio(0); } while (0)
; #define PG8_WAIT_V(n) asm volatile("s_waitcnt vmcnt(" #n ")" ::: "memory")
; #define PG8_WAIT_L(n) asm volatile("s_waitcnt lgkmcnt(" #n ")" ::: "memory")
; #define PG8_BAR __builtin_amdgcn_s_barrier()
; #define PG8_SCHED __builtin_amdgcn_sched_barrier(0)
; template <class Epi, class Sched, bool ALIGN_EPI = false, bool SP2 = false>
; __device__ __forceinline__ void gemm_phase(PG8_LAS unsigned char* lds, const Gemm g, const Sched& S, const Epi& E) {
;     ...
;             PG8_WAIT_V(8); PG8_WAIT_L(0); PG8_BAR; PG8_MMA(0, 0, At, B0); PG8_MMA(0, 1, At, B1); PG8_BAR; PG8_SCHED;
;             PG8_LDA(At, 0, 1); PG8_STAGE(PG8_SB(0, 0), b2, voffB); PG8_STAGE(PG8_SB(0, 1), b2 + hstepB, voffB); PG8_STAGE(PG8_SA(0, 0), a2, voffA);
;             PG8_WAIT_V(8); PG8_WAIT_L(0); PG8_BAR; PG8_MMA(1, 0, At, B0); PG8_MMA(1, 1, At, B1); PG8_BAR; PG8_SCHED;
	s_setprio 1
	s_waitcnt lgkmcnt(0)
	v_mfma_f32_16x16x32_bf16 v[62:65], v[146:149], v[196:199], 0
	v_mfma_f32_16x16x32_bf16 v[62:65], v[168:171], v[200:203], v[62:65]
	v_mfma_f32_16x16x32_bf16 v[58:61], v[176:179], v[200:203], 0
	v_mfma_f32_16x16x32_bf16 v[58:61], v[172:175], v[196:199], v[58:61]
	v_mfma_f32_16x16x32_bf16 v[46:49], v[172:175], v[204:207], 0
	v_mfma_f32_16x16x32_bf16 v[46:49], v[176:179], v[208:211], v[46:49]
	v_mfma_f32_16x16x32_bf16 v[54:57], v[168:171], v[208:211], 0
	v_mfma_f32_16x16x32_bf16 v[54:57], v[146:149], v[204:207], v[54:57]
	v_mfma_f32_16x16x32_bf16 v[38:41], v[146:149], v[212:215], 0
	v_mfma_f32_16x16x32_bf16 v[38:41], v[168:171], v[216:219], v[38:41]
	v_mfma_f32_16x16x32_bf16 v[30:33], v[176:179], v[216:219], 0
	v_mfma_f32_16x16x32_bf16 v[30:33], v[172:175], v[212:215], v[30:33]
	v_mfma_f32_16x16x32_bf16 v[14:17], v[172:175], v[220:223], 0
	v_mfma_f32_16x16x32_bf16 v[14:17], v[176:179], v[224:227], v[14:17]
	v_mfma_f32_16x16x32_bf16 v[22:25], v[168:171], v[224:227], 0
	v_mfma_f32_16x16x32_bf16 v[22:25], v[146:149], v[220:223], v[22:25]
	v_mfma_f32_16x16x32_bf16 v[50:53], v[180:183], v[196:199], 0
	v_mfma_f32_16x16x32_bf16 v[50:53], v[184:187], v[200:203], v[50:53]
	v_mfma_f32_16x16x32_bf16 v[42:45], v[192:195], v[200:203], 0
	v_mfma_f32_16x16x32_bf16 v[42:45], v[188:191], v[196:199], v[42:45]
	v_mfma_f32_16x16x32_bf16 v[26:29], v[188:191], v[204:207], 0
	v_mfma_f32_16x16x32_bf16 v[26:29], v[192:195], v[208:211], v[26:29]
	v_mfma_f32_16x16x32_bf16 v[34:37], v[184:187], v[208:211], 0
	v_mfma_f32_16x16x32_bf16 v[34:37], v[180:183], v[204:207], v[34:37]
	v_mfma_f32_16x16x32_bf16 v[18:21], v[180:183], v[212:215], 0
	v_mfma_f32_16x16x32_bf16 v[18:21], v[184:187], v[216:219], v[18:21]
	v_mfma_f32_16x16x32_bf16 v[10:13], v[192:195], v[216:219], 0
	v_mfma_f32_16x16x32_bf16 v[10:13], v[188:191], v[212:215], v[10:13]
	v_mfma_f32_16x16x32_bf16 v[2:5], v[188:191], v[220:223], 0
	v_mfma_f32_16x16x32_bf16 v[2:5], v[192:195], v[224:227], v[2:5]
	s_setprio 2
	s_barrier
	v_mfma_f32_16x16x32_bf16 v[6:9], v[184:187], v[224:227], 0
	v_mfma_f32_16x16x32_bf16 v[6:9], v[180:183], v[220:223], v[6:9]
	s_setprio 0
	s_add_i32 s61, 0, 0x18000
	v_add_u32_e32 v150, s61, v158
	s_add_i32 s62, 0, 0x1c000
	ds_read_b128 v[146:149], v150
	ds_read_b128 v[168:171], v150 offset:1024
	ds_read_b128 v[172:175], v150 offset:2048
	ds_read_b128 v[176:179], v150 offset:3072
	v_add_u32_e32 v150, s62, v158
	ds_read_b128 v[180:183], v150
	ds_read_b128 v[184:187], v150 offset:1024
	ds_read_b128 v[188:191], v150 offset:2048
	ds_read_b128 v[192:195], v150 offset:3072
	s_add_u32 s26, s26, 0x100000
	s_addc_u32 s27, s27, 0
	s_mov_b32 m0, s31
	ds_read_b128 v[196:199], v162 offset:32768
	ds_read_b128 v[200:203], v162 offset:33792
	ds_read_b128 v[204:207], v162 offset:34816
	ds_read_b128 v[208:211], v162 offset:35840
	ds_read_b128 v[212:215], v162 offset:36864
	ds_read_b128 v[216:219], v162 offset:37888
	ds_read_b128 v[220:223], v162 offset:38912
	ds_read_b128 v[224:227], v162 offset:39936
	global_load_lds_dwordx4 v130, s[26:27]
	s_mov_b32 m0, s33
	s_nop 0
	global_load_lds_dwordx4 v132, s[26:27]
	s_waitcnt vmcnt(8)
	s_waitcnt lgkmcnt(0)
	s_barrier
	s_setprio 1
	s_waitcnt lgkmcnt(0)
	v_mfma_f32_16x16x32_bf16 v[126:129], v[146:149], v[196:199], v[126:129]
	v_mfma_f32_16x16x32_bf16 v[126:129], v[168:171], v[200:203], v[126:129]
	v_mfma_f32_16x16x32_bf16 v[122:125], v[176:179], v[200:203], v[122:125]
	v_mfma_f32_16x16x32_bf16 v[122:125], v[172:175], v[196:199], v[122:125]
	v_mfma_f32_16x16x32_bf16 v[114:117], v[172:175], v[204:207], v[114:117]
	v_mfma_f32_16x16x32_bf16 v[114:117], v[176:179], v[208:211], v[114:117]
	v_mfma_f32_16x16x32_bf16 v[118:121], v[168:171], v[208:211], v[118:121]
	v_mfma_f32_16x16x32_bf16 v[118:121], v[146:149], v[204:207], v[118:121]
	v_mfma_f32_16x16x32_bf16 v[110:113], v[146:149], v[212:215], v[110:113]
	v_mfma_f32_16x16x32_bf16 v[110:113], v[168:171], v[216:219], v[110:113]
	v_mfma_f32_16x16x32_bf16 v[98:101], v[176:179], v[216:219], v[98:101]
	v_mfma_f32_16x16x32_bf16 v[98:101], v[172:175], v[212:215], v[98:101]
	v_mfma_f32_16x16x32_bf16 v[78:81], v[172:175], v[220:223], v[78:81]
	v_mfma_f32_16x16x32_bf16 v[78:81], v[176:179], v[224:227], v[78:81]
	v_mfma_f32_16x16x32_bf16 v[82:85], v[168:171], v[224:227], v[82:85]
	v_mfma_f32_16x16x32_bf16 v[82:85], v[146:149], v[220:223], v[82:85]
	v_mfma_f32_16x16x32_bf16 v[106:109], v[180:183], v[196:199], v[106:109]
	v_mfma_f32_16x16x32_bf16 v[106:109], v[184:187], v[200:203], v[106:109]
	v_mfma_f32_16x16x32_bf16 v[102:105], v[192:195], v[200:203], v[102:105]
	v_mfma_f32_16x16x32_bf16 v[102:105], v[188:191], v[196:199], v[102:105]
	v_mfma_f32_16x16x32_bf16 v[90:93], v[188:191], v[204:207], v[90:93]
	v_mfma_f32_16x16x32_bf16 v[90:93], v[192:195], v[208:211], v[90:93]
	v_mfma_f32_16x16x32_bf16 v[94:97], v[184:187], v[208:211], v[94:97]
	v_mfma_f32_16x16x32_bf16 v[94:97], v[180:183], v[204:207], v[94:97]
	v_mfma_f32_16x16x32_bf16 v[86:89], v[180:183], v[212:215], v[86:89]
	v_mfma_f32_16x16x32_bf16 v[86:89], v[184:187], v[216:219], v[86:89]
	v_mfma_f32_16x16x32_bf16 v[74:77], v[192:195], v[216:219], v[74:77]
	v_mfma_f32_16x16x32_bf16 v[74:77], v[188:191], v[212:215], v[74:77]
	v_mfma_f32_16x16x32_bf16 v[66:69], v[188:191], v[220:223], v[66:69]
	v_mfma_f32_16x16x32_bf16 v[66:69], v[192:195], v[224:227], v[66:69]
	s_setprio 2
	s_barrier
; #define PG8_STAGE(bufoff, gbase, voff) do { _Pragma("unroll") for (int _i = 0; _i < 2; ++_i) \
;         __builtin_amdgcn_global_load_lds((const unsigned*)((const char*)(gbase) + (voff)[_i]), (PG8_LAS unsigned*)(lds + (bufoff) + ldsw + _i * 8192), 16, 0, 0); } while (0)
; #define PG8_LDA(dst, b, h) do { _Pragma("unroll") for (int m = 0; m < 4; ++m) _Pragma("unroll") for (int k = 0; k < 2; ++k) dst[m][k] = *(const PG8_LAS bf16x8*)(lds + PG8_SA(b, h) + aoff + m * 2048 + k * 1024); } while (0)
; #define PG8_BAR __builtin_amdgcn_s_barrier()
; template <class Epi, class Sched, bool ALIGN_EPI = false, bool SP2 = false>
; __device__ __forceinline__ void gemm_phase(PG8_LAS unsigned char* lds, const Gemm g, const Sched& S, const Epi& E) {
;     ...
;         for (int t = 0; t < nt; t += 2) {
;             const bool last = (t == nt - 2);
;             const char* a1 = cA + (size_t)(t + 1) * kstep + (t >= g.kj_t ? g.kj_bytes : 0);
;             const char* a2 = last ? nA : cA + (size_t)(t + 2) * kstep + (t + 2 >= g.kj_t ? g.kj_bytes : 0); const char* b2 = last ? nB : cB + (size_t)(t + 2) * kstep;
;             const char* a3 = a2 + kstep; const char* b3 = b2 + kstep;
;             if (last && has_next) S.a_ready(nxt);
;             if constexpr (Epi::MIDK) { if (t == g.kj_t) E.midk(acc, cur, wr, fr); }
;             if constexpr (SP2) {
;             PG8_LDB(B0, 0, 0); PG8_LDB(B1, 0, 1); PG8_SCHED; PG8_LDA(At, 0, 0); PG8_STAGE(PG8_SA(1, 1), a1 + hstepA, voffA);
;             PG8_WAIT_V(8); PG8_WAIT_L(0); PG8_BAR; PG8_MMA(0, 0, At, B0); PG8_MMA(0, 1, At, B1); PG8_BAR; PG8_SCHED;
;             PG8_LDA(At, 0, 1); PG8_STAGE(PG8_SB(0, 0), b2, voffB); PG8_STAGE(PG8_SB(0, 1), b2 + hstepB, voffB); PG8_STAGE(PG8_SA(0, 0), a2, voffA);
;             PG8_WAIT_V(8); PG8_WAIT_L(0); PG8_BAR; PG8_MMA(1, 0, At, B0); PG8_MMA(1, 1, At, B1); PG8_BAR; PG8_SCHED;
;             PG8_LDB(B0, 1, 0); PG8_LDB(B1, 1, 1); PG8_SCHED; PG8_LDA(At, 1, 0); PG8_STAGE(PG8_SA(0, 1), a2 + hstepA, voffA);
;             PG8_WAIT_V(8); PG8_WAIT_L(0); PG8_BAR; PG8_MMA(0, 0, At, B0); PG8_MMA(0, 1, At, B1); PG8_BAR; PG8_SCHED;
;             PG8_LDA(At, 1, 1); PG8_STAGE(PG8_SB(1, 0), b3, voffB); PG8_STAGE(PG8_SB(1, 1), b3 + hstepB, voffB); PG8_STAGE(PG8_SA(1, 0), a3, voffA);
;             PG8_WAIT_V(8); PG8_WAIT_L(0); PG8_BAR; PG8_MMA(1, 0, At, B0); PG8_MMA(1, 1, At, B1); PG8_BAR; PG8_SCHED;
	v_mfma_f32_16x16x32_bf16 v[70:73], v[184:187], v[224:227], v[70:73]
	v_mfma_f32_16x16x32_bf16 v[70:73], v[180:183], v[220:223], v[70:73]
	s_setprio 0
	s_add_i32 s26, s61, s3
	s_mov_b32 m0, s26
	ds_read_b128 v[196:199], v162 offset:49152
	ds_read_b128 v[200:203], v162 offset:50176
	ds_read_b128 v[204:207], v162 offset:51200
	ds_read_b128 v[208:211], v162 offset:52224
	ds_read_b128 v[212:215], v162 offset:53248
	ds_read_b128 v[216:219], v162 offset:54272
	ds_read_b128 v[220:223], v162 offset:55296
	ds_read_b128 v[224:227], v162 offset:56320
	global_load_lds_dwordx4 v136, s[98:99]
	s_add_i32 m0, s26, 0x2000
	s_add_u32 s24, s24, 0x100080
	s_addc_u32 s25, s25, 0
	s_add_i32 s26, s62, s3
	global_load_lds_dwordx4 v134, s[98:99]
	s_mov_b32 m0, s26
	s_nop 0
	global_load_lds_dwordx4 v136, s[24:25]
	s_add_i32 m0, s26, 0x2000
	s_nop 0
	global_load_lds_dwordx4 v134, s[24:25]
	s_mov_b32 m0, s35
	s_nop 0
	global_load_lds_dwordx4 v130, s[100:101]
	s_mov_b32 m0, s36
	s_nop 0
	global_load_lds_dwordx4 v132, s[100:101]
	s_waitcnt vmcnt(8)
	s_waitcnt lgkmcnt(0)
	s_barrier
	s_setprio 1
	s_waitcnt lgkmcnt(0)
	v_mfma_f32_16x16x32_bf16 v[62:65], v[146:149], v[196:199], v[62:65]
	v_mfma_f32_16x16x32_bf16 v[62:65], v[168:171], v[200:203], v[62:65]
	v_mfma_f32_16x16x32_bf16 v[58:61], v[176:179], v[200:203], v[58:61]
	v_mfma_f32_16x16x32_bf16 v[58:61], v[172:175], v[196:199], v[58:61]
	v_mfma_f32_16x16x32_bf16 v[46:49], v[172:175], v[204:207], v[46:49]
	v_mfma_f32_16x16x32_bf16 v[46:49], v[176:179], v[208:211], v[46:49]
	v_mfma_f32_16x16x32_bf16 v[54:57], v[168:171], v[208:211], v[54:57]
	v_mfma_f32_16x16x32_bf16 v[54:57], v[146:149], v[204:207], v[54:57]
	v_mfma_f32_16x16x32_bf16 v[38:41], v[146:149], v[212:215], v[38:41]
	v_mfma_f32_16x16x32_bf16 v[38:41], v[168:171], v[216:219], v[38:41]
	v_mfma_f32_16x16x32_bf16 v[30:33], v[176:179], v[216:219], v[30:33]
	v_mfma_f32_16x16x32_bf16 v[30:33], v[172:175], v[212:215], v[30:33]
	v_mfma_f32_16x16x32_bf16 v[14:17], v[172:175], v[220:223], v[14:17]
	v_mfma_f32_16x16x32_bf16 v[14:17], v[176:179], v[224:227], v[14:17]
	v_mfma_f32_16x16x32_bf16 v[22:25], v[168:171], v[224:227], v[22:25]
	v_mfma_f32_16x16x32_bf16 v[22:25], v[146:149], v[220:223], v[22:25]
	v_mfma_f32_16x16x32_bf16 v[50:53], v[180:183], v[196:199], v[50:53]
	v_mfma_f32_16x16x32_bf16 v[50:53], v[184:187], v[200:203], v[50:53]
	v_mfma_f32_16x16x32_bf16 v[42:45], v[192:195], v[200:203], v[42:45]
	v_mfma_f32_16x16x32_bf16 v[42:45], v[188:191], v[196:199], v[42:45]
	v_mfma_f32_16x16x32_bf16 v[26:29], v[188:191], v[204:207], v[26:29]
	v_mfma_f32_16x16x32_bf16 v[26:29], v[192:195], v[208:211], v[26:29]
	v_mfma_f32_16x16x32_bf16 v[34:37], v[184:187], v[208:211], v[34:37]
	v_mfma_f32_16x16x32_bf16 v[34:37], v[180:183], v[204:207], v[34:37]
	v_mfma_f32_16x16x32_bf16 v[18:21], v[180:183], v[212:215], v[18:21]
	v_mfma_f32_16x16x32_bf16 v[18:21], v[184:187], v[216:219], v[18:21]
	v_mfma_f32_16x16x32_bf16 v[10:13], v[192:195], v[216:219], v[10:13]
	v_mfma_f32_16x16x32_bf16 v[10:13], v[188:191], v[212:215], v[10:13]
	v_mfma_f32_16x16x32_bf16 v[2:5], v[188:191], v[220:223], v[2:5]
	v_mfma_f32_16x16x32_bf16 v[2:5], v[192:195], v[224:227], v[2:5]
	s_setprio 2
	s_barrier
	v_mfma_f32_16x16x32_bf16 v[6:9], v[184:187], v[224:227], v[6:9]
	v_mfma_f32_16x16x32_bf16 v[6:9], v[180:183], v[220:223], v[6:9]
	s_setprio 0
	s_add_i32 s60, s60, 2
	s_add_u32 s22, s22, 0x100
	s_addc_u32 s23, s23, 0
	s_add_u32 s52, s52, 0x100
	s_addc_u32 s53, s53, 0
